# forgetting attention: PV MFMAs interleaved with exp VALU in the common path
# baseline (speedup 1.0000x reference)
; #define MFMA32(a, b, c) __builtin_amdgcn_mfma_f32_32x32x16_bf16((a), (b), (c), 0, 0, 0)
; DI unsigned pk2(float a, float b) { f2_t v = {a, b}; bf2_t r = __builtin_convertvector(v, bf2_t); return __builtin_bit_cast(unsigned, r); }
; DI float ex2(float x) { return __builtin_amdgcn_exp2f(x); }
; DI float shx32(float v) { return shx(v, get_tid() & 63, 32); }
; template <int MODE>
; DI void attn_item(const CP& p, int l, int b, int head, int qt, char* smem) {
;     ...
;           for (int rb = 0; rb < 2; ++rb)
; #pragma unroll
;             for (int r = 0; r < 16; ++r) { const float e = ex2(s[rb][r]); s[rb][r] = e; sum += e; }
;           sum += shx32(sum);
;           lsum += sum;
;     ...
;       bf16x8 pf[4];
; #pragma unroll
;       for (int j = 0; j < 4; ++j) {
;         const int rb = j >> 1, r0 = (j & 1) * 8;
;         u32x4 u;
;         u.x = pk2(s[rb][r0], s[rb][r0 + 1]);
;         u.y = pk2(s[rb][r0 + 2], s[rb][r0 + 3]);
;         u.z = pk2(s[rb][r0 + 4], s[rb][r0 + 5]);
;         u.w = pk2(s[rb][r0 + 6], s[rb][r0 + 7]);
;         pf[j] = __builtin_bit_cast(bf16x8, u);
;       }
; #pragma unroll
;       for (int db = 0; db < 2; ++db)
; #pragma unroll
;         for (int j = 0; j < 4; ++j) {
;           const u16* vp = cV + (db * 32 + l32) * 72 + 16 * j + 4 * hh;
;           u32x2 lo = *(const u32x2*)(vp);
;           u32x2 hi = *(const u32x2*)(vp + 8);
;           u32x4 u = {lo.x, lo.y, hi.x, hi.y};
;           o[db] = MFMA32(__builtin_bit_cast(bf16x8, u), pf[j], o[db]);
;         }
.Lfx_norescale:
	v_exp_f32_e32 v0, v66
	v_exp_f32_e32 v1, v67
	v_exp_f32_e32 v2, v68
	v_exp_f32_e32 v3, v69
	v_add_f32_e32 v4, 0, v0
	v_add_f32_e32 v4, v1, v4
	v_add_f32_e32 v4, v2, v4
	v_add_f32_e32 v8, v3, v4
	v_exp_f32_e32 v4, v70
	v_exp_f32_e32 v5, v71
	v_exp_f32_e32 v6, v72
	v_exp_f32_e32 v7, v73
	v_add_f32_e32 v8, v4, v8
	v_add_f32_e32 v8, v5, v8
	v_add_f32_e32 v8, v6, v8
	v_add_f32_e32 v12, v7, v8
	v_cvt_pk_bf16_f32 v0, v0, v1
	v_cvt_pk_bf16_f32 v1, v2, v3
	v_cvt_pk_bf16_f32 v2, v4, v5
	v_cvt_pk_bf16_f32 v3, v6, v7
	v_exp_f32_e32 v8, v74
	v_exp_f32_e32 v9, v75
	v_exp_f32_e32 v10, v76
	v_exp_f32_e32 v11, v77
	s_waitcnt lgkmcnt(0)
	v_mfma_f32_32x32x16_bf16 v[50:65], v[216:219], v[0:3], v[50:65]
	v_mfma_f32_32x32x16_bf16 v[34:49], v[232:235], v[0:3], v[34:49]
	v_add_f32_e32 v12, v8, v12
	v_add_f32_e32 v12, v9, v12
	v_add_f32_e32 v12, v10, v12
	v_add_f32_e32 v16, v11, v12
	v_exp_f32_e32 v12, v78
	v_exp_f32_e32 v13, v79
	v_exp_f32_e32 v14, v80
	v_exp_f32_e32 v15, v81
	v_add_f32_e32 v16, v12, v16
	v_add_f32_e32 v16, v13, v16
	v_add_f32_e32 v16, v14, v16
	v_add_f32_e32 v20, v15, v16
	v_cvt_pk_bf16_f32 v4, v8, v9
	v_cvt_pk_bf16_f32 v5, v10, v11
	v_cvt_pk_bf16_f32 v6, v12, v13
	v_cvt_pk_bf16_f32 v7, v14, v15
	v_exp_f32_e32 v16, v82
	v_exp_f32_e32 v17, v83
	v_exp_f32_e32 v18, v84
	v_exp_f32_e32 v19, v85
	v_mfma_f32_32x32x16_bf16 v[50:65], v[220:223], v[4:7], v[50:65]
	v_mfma_f32_32x32x16_bf16 v[34:49], v[236:239], v[4:7], v[34:49]
	v_add_f32_e32 v20, v16, v20
	v_add_f32_e32 v20, v17, v20
	v_add_f32_e32 v20, v18, v20
	v_add_f32_e32 v24, v19, v20
	v_exp_f32_e32 v20, v86
	v_exp_f32_e32 v21, v87
	v_exp_f32_e32 v22, v88
	v_exp_f32_e32 v23, v89
	v_add_f32_e32 v24, v20, v24
	v_add_f32_e32 v24, v21, v24
	v_add_f32_e32 v24, v22, v24
	v_add_f32_e32 v28, v23, v24
	v_cvt_pk_bf16_f32 v8, v16, v17
	v_cvt_pk_bf16_f32 v9, v18, v19
	v_cvt_pk_bf16_f32 v10, v20, v21
	v_cvt_pk_bf16_f32 v11, v22, v23
	v_exp_f32_e32 v24, v90
	v_exp_f32_e32 v25, v91
	v_exp_f32_e32 v26, v92
	v_exp_f32_e32 v27, v93
	v_mfma_f32_32x32x16_bf16 v[50:65], v[224:227], v[8:11], v[50:65]
	v_mfma_f32_32x32x16_bf16 v[34:49], v[240:243], v[8:11], v[34:49]
	v_add_f32_e32 v28, v24, v28
	v_add_f32_e32 v28, v25, v28
	v_add_f32_e32 v28, v26, v28
	v_add_f32_e32 v32, v27, v28
	v_exp_f32_e32 v28, v94
	v_exp_f32_e32 v29, v95
	v_exp_f32_e32 v30, v96
	v_exp_f32_e32 v31, v97
	v_add_f32_e32 v32, v28, v32
	v_add_f32_e32 v32, v29, v32
	v_add_f32_e32 v32, v30, v32
	v_add_f32_e32 v32, v31, v32
	v_cvt_pk_bf16_f32 v12, v24, v25
	v_cvt_pk_bf16_f32 v13, v26, v27
	v_cvt_pk_bf16_f32 v14, v28, v29
	v_cvt_pk_bf16_f32 v15, v30, v31
	v_mov_b32_e32 v66, v32
	s_nop 1
	v_permlane32_swap_b32_e32 v32, v66
	v_add_f32_e32 v32, v32, v66
	v_add_f32_e32 v176, v176, v32
	v_mov_b64_e32 v[178:179], v[176:177]
	v_mfma_f32_32x32x16_bf16 v[50:65], v[228:231], v[12:15], v[50:65]
	v_mfma_f32_32x32x16_bf16 v[34:49], v[244:247], v[12:15], v[34:49]
	s_andn2_b64 s[72:73], s[72:73], exec
	v_mov_b64_e32 v[176:177], v[178:179]
	s_branch .LBB0_367
